# adds: odd_prep MLA row loads at item start, pass A load merge, GLA pass B final wave sums on DPP
# speedup vs baseline: 1.0172x; 1.0027x over previous
.LBB0_541:
	s_load_dwordx2 s[96:97], s[8:9], 0xf8
	s_load_dwordx2 s[98:99], s[8:9], 0x108
	v_lshrrev_b32_e32 v122, 6, v202
	s_lshl_b32 s4, s7, 4
	v_and_b32_e32 v124, 63, v202
	v_add_u32_e32 v122, s4, v122
	v_mov_b32_e32 v123, 0
	v_lshlrev_b32_e32 v122, 12, v122
	v_mov_b32_e32 v127, 0
	v_lshl_add_u64 v[122:123], s[80:81], 0, v[122:123]
	v_lshlrev_b32_e32 v126, 3, v124
	v_add_co_u32_e32 v122, vcc, 0x2448000, v122
	s_nop 1
	v_addc_co_u32_e32 v123, vcc, 0, v123, vcc
	s_nop 0
	v_lshl_add_u64 v[126:127], v[122:123], 0, v[126:127]
	s_nop 0
	v_add_co_u32_e32 v128, vcc, 0x8000, v126
	global_load_dwordx2 v[106:107], v[126:127], off offset:3072
	v_addc_co_u32_e32 v129, vcc, 0, v127, vcc
	v_lshlrev_b32_e32 v126, 2, v124
	v_mov_b32_e32 v127, 0
	global_load_dwordx2 v[110:111], v[128:129], off offset:3072
	v_lshl_add_u64 v[126:127], v[122:123], 0, v[126:127]
	s_nop 0
	v_add_co_u32_e32 v128, vcc, 0x8000, v126
	global_load_dword v108, v[126:127], off offset:3584
	v_addc_co_u32_e32 v129, vcc, 0, v127, vcc
	v_lshlrev_b32_e32 v126, 1, v124
	v_mov_b32_e32 v127, 0
	global_load_dword v112, v[128:129], off offset:3584
	v_lshl_add_u64 v[126:127], v[122:123], 0, v[126:127]
	s_nop 0
	v_add_co_u32_e32 v128, vcc, 0x8000, v126
	global_load_ushort v109, v[126:127], off offset:3840
	v_addc_co_u32_e32 v129, vcc, 0, v127, vcc
	s_nop 1
	global_load_ushort v113, v[128:129], off offset:3840
	v_mov_b32_e32 v130, s58
	v_mov_b32_e32 v131, s58
	v_lshlrev_b32_e32 v130, 10, v130
	v_lshlrev_b32_e32 v131, 9, v131
	v_lshl_add_u32 v130, v124, 4, v130
	v_lshl_add_u32 v131, v124, 3, v131
	v_mov_b32_e32 v2, v202
	s_load_dwordx4 s[44:47], s[8:9], 0xb0
	s_mul_i32 s4, s58, 0x600
	v_add_u32_e32 v8, s4, v2
	v_ashrrev_i32_e32 v3, 31, v2
	v_readlane_b32 s4, v254, 55
	s_waitcnt lgkmcnt(0)
	global_load_dwordx4 v[100:103], v130, s[96:97]
	global_load_dwordx2 v[104:105], v131, s[98:99]
	v_mov_b32_e32 v4, s44
	v_mov_b32_e32 v5, s45
	v_lshl_add_u64 v[4:5], v[2:3], 2, v[4:5]
	v_readlane_b32 s5, v254, 56
	v_ashrrev_i32_e32 v9, 31, v8
	v_lshl_add_u64 v[42:43], v[8:9], 2, s[46:47]
	v_lshl_add_u64 v[6:7], v[4:5], 0, s[4:5]
	v_add_co_u32_e32 v4, vcc, 0x1000, v6
	global_load_dword v0, v[42:43], off
	s_nop 0
	v_addc_co_u32_e32 v5, vcc, 0, v7, vcc
	v_add_co_u32_e32 v10, vcc, 0x3000, v6
	s_lshl_b32 s44, s7, 4
	s_nop 0
	v_addc_co_u32_e32 v11, vcc, 0, v7, vcc
	global_load_dword v9, v[6:7], off
	global_load_dword v45, v[4:5], off offset:2048
	global_load_dword v44, v[10:11], off
	s_cmpk_lt_i32 s7, 0x100
	s_cselect_b64 s[14:15], -1, 0
	s_and_b64 s[10:11], s[14:15], exec
	s_movk_i32 s4, 0xf0
	s_cselect_b32 s4, s4, 0x3f0
	s_and_b32 s10, s4, s44
	s_cmp_lg_u32 s10, 0
	v_readlane_b32 s4, v254, 37
	s_cselect_b64 s[42:43], -1, 0
	s_add_i32 s82, s44, -1
	v_readlane_b32 s5, v254, 38
	s_cmp_eq_u32 s10, 0
	v_mov_b32_e32 v46, 0
	v_lshl_add_u64 v[4:5], v[2:3], 1, s[4:5]
	v_mov_b32_e32 v72, 0
	s_cbranch_scc1 .LBB0_543
	s_ashr_i32 s83, s82, 31
	s_lshl_b64 s[18:19], s[82:83], 12
	v_lshl_add_u64 v[10:11], v[4:5], 0, s[18:19]
	global_load_ushort v72, v[10:11], off

.LBB0_567:
	s_load_dwordx2 s[0:1], s[8:9], 0x88
	v_readlane_b32 s3, v254, 43
	v_lshlrev_b32_e32 v4, 2, v20
	v_add_u32_e32 v5, 0, v4
	v_or_b32_e32 v0, s3, v20
	s_waitcnt lgkmcnt(0)
	v_lshl_add_u64 v[2:3], v[0:1], 2, s[0:1]
	global_load_dword v17, v[2:3], off
	global_load_dword v16, v[2:3], off offset:256
	v_and_b32_e32 v0, 64, v210
	v_add_u32_e32 v0, 64, v0
	v_xor_b32_e32 v2, 32, v210
	v_cmp_lt_i32_e32 vcc, v2, v0
	s_movk_i32 s0, 0x1080
	v_xor_b32_e32 v13, 2, v210
	v_cndmask_b32_e32 v2, v210, v2, vcc
	v_lshlrev_b32_e32 v25, 2, v2
	v_xor_b32_e32 v2, 16, v210
	v_cmp_lt_i32_e32 vcc, v2, v0
	v_readlane_b32 s4, v253, 50
	v_readlane_b32 s5, v253, 51
	v_cndmask_b32_e32 v2, v210, v2, vcc
	v_lshlrev_b32_e32 v24, 2, v2
	v_xor_b32_e32 v2, 8, v210
	v_cmp_lt_i32_e32 vcc, v2, v0
	s_mov_b32 s87, 0x800000
	v_lshlrev_b64 v[18:19], 11, v[18:19]
	v_cndmask_b32_e32 v2, v210, v2, vcc
	v_lshlrev_b32_e32 v23, 2, v2
	v_xor_b32_e32 v2, 4, v210
	v_cmp_lt_i32_e32 vcc, v2, v0
	v_add_u32_e32 v28, s18, v84
	v_ashrrev_i32_e32 v29, 31, v28
	v_cndmask_b32_e32 v2, v210, v2, vcc
	v_lshlrev_b32_e32 v22, 2, v2
	v_mul_lo_u32 v2, v83, s0
	v_add_u32_e32 v3, v5, v2
	v_add3_u32 v2, 0, v2, v4
	ds_read_b32 v6, v3
	ds_read_b32 v7, v2 offset:256
	v_mul_lo_u32 v2, v84, s29
	v_add3_u32 v12, 0, v2, v4
	v_add_u32_e32 v3, v5, v2
	ds_read2_b32 v[8:9], v12 offset0:64 offset1:132
	ds_read_b32 v10, v3
	s_waitcnt lgkmcnt(2)
	v_pk_mul_f32 v[2:3], v[6:7], v[6:7]
	v_cmp_lt_i32_e32 vcc, v13, v0
	v_mov_b32_e32 v15, v2
	s_waitcnt lgkmcnt(1)
	v_mov_b32_e32 v11, v8
	s_waitcnt lgkmcnt(0)
	v_pk_mul_f32 v[4:5], v[10:11], v[10:11]
	v_cndmask_b32_e32 v11, v210, v13, vcc
	v_mov_b32_e32 v14, v4
	v_mov_b32_e32 v2, v5
	v_pk_add_f32 v[2:3], v[14:15], v[2:3]
	s_nop 1
	v_add_f32_dpp v242, v2, v2 quad_perm:[1,0,3,2] row_mask:0xf bank_mask:0xf
	s_nop 1
	v_add_f32_dpp v242, v242, v242 quad_perm:[2,3,0,1] row_mask:0xf bank_mask:0xf
	s_nop 1
	v_add_f32_dpp v242, v242, v242 row_ror:4 row_mask:0xf bank_mask:0xf
	s_nop 1
	v_add_f32_dpp v242, v242, v242 row_ror:8 row_mask:0xf bank_mask:0xf
	s_nop 1
	v_readlane_b32 s96, v242, 0
	v_readlane_b32 s97, v242, 16
	v_readlane_b32 s98, v242, 32
	v_readlane_b32 s99, v242, 48
	v_mov_b32_e32 v240, s96
	v_add_f32_e32 v240, s97, v240
	v_add_f32_e32 v240, s98, v240
	v_add_f32_e32 v240, s99, v240
	v_add_f32_dpp v243, v3, v3 quad_perm:[1,0,3,2] row_mask:0xf bank_mask:0xf
	s_nop 1
	v_add_f32_dpp v243, v243, v243 quad_perm:[2,3,0,1] row_mask:0xf bank_mask:0xf
	s_nop 1
	v_add_f32_dpp v243, v243, v243 row_ror:4 row_mask:0xf bank_mask:0xf
	s_nop 1
	v_add_f32_dpp v243, v243, v243 row_ror:8 row_mask:0xf bank_mask:0xf
	s_nop 1
	v_readlane_b32 s96, v243, 0
	v_readlane_b32 s97, v243, 16
	v_readlane_b32 s98, v243, 32
	v_readlane_b32 s99, v243, 48
	v_mov_b32_e32 v241, s96
	v_add_f32_e32 v241, s97, v241
	v_add_f32_e32 v241, s98, v241
	v_add_f32_e32 v241, s99, v241
	v_lshlrev_b32_e32 v27, 2, v11
	v_xor_b32_e32 v11, 1, v210
	v_cmp_lt_i32_e32 vcc, v11, v0
	v_readlane_b32 s0, v255, 0
	s_waitcnt lgkmcnt(0)
	v_cndmask_b32_e32 v0, v210, v11, vcc
	v_lshlrev_b32_e32 v11, 16, v80
	v_lshlrev_b32_e32 v26, 2, v0
	v_mul_f32_e32 v0, 0xbfb8aa3b, v11
	s_waitcnt lgkmcnt(0)
	v_exp_f32_e32 v13, v0
	s_lshl_b32 s0, s0, 1
	s_add_u32 s0, s4, s0
	s_addc_u32 s1, s5, 0
	s_waitcnt lgkmcnt(0)
	v_lshlrev_b32_e32 v0, 1, v20
	v_lshl_add_u64 v[2:3], s[0:1], 0, v[0:1]
	v_add_f32_e32 v0, 1.0, v13
	v_rcp_f32_e32 v0, v0
	s_waitcnt lgkmcnt(0)
	v_lshlrev_b32_e32 v13, 16, v79
	v_mul_f32_e32 v0, v0, v11
	v_mul_f32_e32 v11, 0xbfb8aa3b, v13
	v_exp_f32_e32 v11, v11
	s_waitcnt lgkmcnt(0)
	s_mov_b32 s0, 0x358637bd
	v_add_f32_e32 v11, 1.0, v11
	v_rcp_f32_e32 v11, v11
	v_lshl_add_u64 v[18:19], v[2:3], 0, v[18:19]
	s_waitcnt lgkmcnt(0)
	v_mov_b32_e32 v14, v240
	v_mov_b32_e32 v15, v241
	v_mov_b64_e32 v[4:5], s[0:1]
	s_brev_b32 s0, 60
	v_pk_fma_f32 v[14:15], v[14:15], s[0:1], v[4:5] op_sel_hi:[1,0,0]
	v_mul_f32_e32 v11, v11, v13
	v_mul_f32_e32 v20, 0x4b800000, v15
	v_cmp_gt_f32_e32 vcc, s87, v15
	v_cmp_gt_f32_e64 s[40:41], s87, v14
	v_readlane_b32 s92, v253, 28
	v_cndmask_b32_e32 v15, v15, v20, vcc
	v_rsq_f32_e32 v15, v15
	v_readlane_b32 s70, v254, 34
	v_readlane_b32 s74, v254, 37
	v_readlane_b32 s58, v254, 44
	v_mul_f32_e32 v13, 0x45800000, v15
	v_cndmask_b32_e32 v13, v15, v13, vcc
	v_mul_f32_e32 v6, v6, v13
	s_waitcnt vmcnt(1)
	v_mul_f32_e32 v6, v17, v6
	v_mul_f32_e32 v0, v0, v6
	v_bfe_u32 v6, v0, 16, 1
	v_add3_u32 v0, v0, v6, s27
	global_store_short_d16_hi v[18:19], v0, off
	v_mul_f32_e32 v0, v7, v13
	s_waitcnt vmcnt(1)
	v_mul_f32_e32 v0, v16, v0
	v_mul_f32_e32 v0, v11, v0
	v_bfe_u32 v6, v0, 16, 1
	v_add3_u32 v0, v0, v6, s27
	v_mul_f32_e32 v6, 0x4b800000, v14
	v_cndmask_b32_e64 v6, v14, v6, s[40:41]
	v_lshlrev_b32_e32 v7, 16, v78
	v_rsq_f32_e32 v6, v6
	v_mul_f32_e32 v11, 0xbfb8aa3b, v7
	v_exp_f32_e32 v11, v11
	global_store_short_d16_hi v[18:19], v0, off offset:128
	v_mul_f32_e32 v0, 0x45800000, v6
	v_cndmask_b32_e64 v0, v6, v0, s[40:41]
	v_add_f32_e32 v6, 1.0, v11
	v_rcp_f32_e32 v6, v6
	v_mul_f32_e32 v10, v10, v0
	v_mul_f32_e32 v10, v17, v10
	v_lshlrev_b32_e32 v13, 16, v76
	v_mul_f32_e32 v6, v6, v7
	v_mul_f32_e32 v6, v6, v10
	v_bfe_u32 v7, v6, 16, 1
	v_add3_u32 v10, v6, v7, s27
	v_lshlrev_b64 v[6:7], 11, v[28:29]
	v_lshl_add_u64 v[6:7], v[2:3], 0, v[6:7]
	v_mul_f32_e32 v14, 0xbfb8aa3b, v13
	global_store_short_d16_hi v[6:7], v10, off
	v_add_u32_e32 v10, 0x200, v12
	v_exp_f32_e32 v20, v14
	v_add_u32_e32 v14, 0x400, v12
	ds_read2_b32 v[10:11], v10 offset0:68 offset1:136
	ds_read2_b32 v[14:15], v14 offset0:72 offset1:140
	v_mov_b32_e32 v18, v9
	v_mul_f32_e32 v0, v8, v0
	v_add_f32_e32 v8, 1.0, v20
	s_waitcnt lgkmcnt(1)
	v_mov_b32_e32 v19, v10
	v_mov_b32_e32 v28, v11
	s_waitcnt lgkmcnt(0)
	v_mov_b32_e32 v29, v14
	v_pk_mul_f32 v[18:19], v[18:19], v[18:19]
	v_pk_mul_f32 v[28:29], v[28:29], v[28:29]
	v_mov_b32_e32 v31, v18
	v_mov_b32_e32 v30, v28
	v_mov_b32_e32 v18, v29
	v_pk_add_f32 v[18:19], v[30:31], v[18:19]
	s_nop 1
	v_add_f32_dpp v242, v18, v18 quad_perm:[1,0,3,2] row_mask:0xf bank_mask:0xf
	s_nop 1
	v_add_f32_dpp v242, v242, v242 quad_perm:[2,3,0,1] row_mask:0xf bank_mask:0xf
	s_nop 1
	v_add_f32_dpp v242, v242, v242 row_ror:4 row_mask:0xf bank_mask:0xf
	s_nop 1
	v_add_f32_dpp v242, v242, v242 row_ror:8 row_mask:0xf bank_mask:0xf
	s_nop 1
	v_readlane_b32 s96, v242, 0
	v_readlane_b32 s97, v242, 16
	v_readlane_b32 s98, v242, 32
	v_readlane_b32 s99, v242, 48
	v_mov_b32_e32 v240, s96
	v_add_f32_e32 v240, s97, v240
	v_add_f32_e32 v240, s98, v240
	v_add_f32_e32 v240, s99, v240
	v_add_f32_dpp v243, v19, v19 quad_perm:[1,0,3,2] row_mask:0xf bank_mask:0xf
	s_nop 1
	v_add_f32_dpp v243, v243, v243 quad_perm:[2,3,0,1] row_mask:0xf bank_mask:0xf
	s_nop 1
	v_add_f32_dpp v243, v243, v243 row_ror:4 row_mask:0xf bank_mask:0xf
	s_nop 1
	v_add_f32_dpp v243, v243, v243 row_ror:8 row_mask:0xf bank_mask:0xf
	s_nop 1
	v_readlane_b32 s96, v243, 0
	v_readlane_b32 s97, v243, 16
	v_readlane_b32 s98, v243, 32
	v_readlane_b32 s99, v243, 48
	v_mov_b32_e32 v241, s96
	v_add_f32_e32 v241, s97, v241
	v_add_f32_e32 v241, s98, v241
	v_add_f32_e32 v241, s99, v241
	v_rcp_f32_e32 v8, v8
	v_mul_f32_e32 v0, v16, v0
	v_readlane_b32 s56, v254, 32
	s_mov_b32 s57, 0xe0000
	s_waitcnt lgkmcnt(0)
	v_mul_f32_e32 v8, v8, v13
	v_mul_f32_e32 v0, v8, v0
	v_bfe_u32 v8, v0, 16, 1
	v_add3_u32 v0, v0, v8, s27
	s_waitcnt lgkmcnt(0)
	global_store_short_d16_hi v[6:7], v0, off offset:128
	v_lshlrev_b32_e32 v0, 16, v74
	v_mul_f32_e32 v6, 0xbfb8aa3b, v0
	v_exp_f32_e32 v8, v6
	s_waitcnt lgkmcnt(0)
	v_add_f32_e32 v8, 1.0, v8
	v_rcp_f32_e32 v8, v8
	v_lshlrev_b32_e32 v13, 16, v73
	v_add_u32_e32 v28, s18, v82
	s_waitcnt lgkmcnt(0)
	v_mul_f32_e32 v0, v8, v0
	v_mul_f32_e32 v8, 0xbfb8aa3b, v13
	v_exp_f32_e32 v8, v8
	v_ashrrev_i32_e32 v29, 31, v28
	s_waitcnt lgkmcnt(0)
	v_add_f32_e32 v8, 1.0, v8
	v_rcp_f32_e32 v8, v8
	v_lshlrev_b64 v[28:29], 11, v[28:29]
	v_lshl_add_u64 v[28:29], v[2:3], 0, v[28:29]
	s_waitcnt lgkmcnt(0)
	v_mov_b32_e32 v6, v240
	v_mov_b32_e32 v7, v241
	v_mul_f32_e32 v13, v8, v13
	v_pk_fma_f32 v[6:7], v[6:7], s[0:1], v[4:5] op_sel_hi:[1,0,0]
	v_add_u32_e32 v8, s18, v81
	v_mul_f32_e32 v18, 0x4b800000, v7
	v_cmp_gt_f32_e32 vcc, s87, v7
	v_cmp_gt_f32_e64 s[40:41], s87, v6
	s_movk_i32 s84, 0x104
	v_cndmask_b32_e32 v7, v7, v18, vcc
	v_rsq_f32_e32 v7, v7
	v_readlane_b32 s69, v253, 27
	s_movk_i32 s68, 0x3000
	s_mov_b32 s86, 0x5040100
	v_mul_f32_e32 v18, 0x45800000, v7
	v_cndmask_b32_e32 v7, v7, v18, vcc
	v_mul_f32_e32 v9, v9, v7
	v_mul_f32_e32 v9, v17, v9
	v_mul_f32_e32 v0, v0, v9
	v_bfe_u32 v9, v0, 16, 1
	v_add3_u32 v0, v0, v9, s27
	global_store_short_d16_hi v[28:29], v0, off
	v_mul_f32_e32 v0, v10, v7
	v_mul_f32_e32 v0, v16, v0
	v_mul_f32_e32 v0, v13, v0
	v_bfe_u32 v7, v0, 16, 1
	v_add3_u32 v0, v0, v7, s27
	v_mul_f32_e32 v7, 0x4b800000, v6
	v_cndmask_b32_e64 v6, v6, v7, s[40:41]
	v_lshlrev_b32_e32 v7, 16, v72
	v_rsq_f32_e32 v6, v6
	v_mul_f32_e32 v9, 0xbfb8aa3b, v7
	v_exp_f32_e32 v9, v9
	global_store_short_d16_hi v[28:29], v0, off offset:128
	v_mul_f32_e32 v0, 0x45800000, v6
	v_cndmask_b32_e64 v0, v6, v0, s[40:41]
	v_add_f32_e32 v6, 1.0, v9
	v_rcp_f32_e32 v6, v6
	v_mul_f32_e32 v9, v11, v0
	v_mul_f32_e32 v9, v17, v9
	v_lshlrev_b32_e32 v13, 16, v71
	v_mul_f32_e32 v6, v6, v7
	v_mul_f32_e32 v6, v6, v9
	v_bfe_u32 v7, v6, 16, 1
	v_ashrrev_i32_e32 v9, 31, v8
	v_add3_u32 v10, v6, v7, s27
	v_lshlrev_b64 v[6:7], 11, v[8:9]
	v_lshl_add_u64 v[8:9], v[2:3], 0, v[6:7]
	v_mul_f32_e32 v6, 0xbfb8aa3b, v13
	v_add_u32_e32 v7, 0x600, v12
	v_exp_f32_e32 v20, v6
	v_add_u32_e32 v6, 0x800, v12
	global_store_short_d16_hi v[8:9], v10, off
	ds_read2_b32 v[10:11], v7 offset0:76 offset1:144
	ds_read2_b32 v[6:7], v6 offset0:80 offset1:148
	v_mov_b32_e32 v18, v15
	v_mul_f32_e32 v0, v14, v0
	v_add_f32_e32 v14, 1.0, v20
	s_waitcnt lgkmcnt(1)
	v_mov_b32_e32 v19, v10
	v_mov_b32_e32 v28, v11
	s_waitcnt lgkmcnt(0)
	v_mov_b32_e32 v29, v6
	v_pk_mul_f32 v[18:19], v[18:19], v[18:19]
	v_pk_mul_f32 v[28:29], v[28:29], v[28:29]
	v_mov_b32_e32 v31, v18
	v_mov_b32_e32 v30, v28
	v_mov_b32_e32 v18, v29
	v_pk_add_f32 v[18:19], v[30:31], v[18:19]
	s_nop 1
	v_add_f32_dpp v242, v18, v18 quad_perm:[1,0,3,2] row_mask:0xf bank_mask:0xf
	s_nop 1
	v_add_f32_dpp v242, v242, v242 quad_perm:[2,3,0,1] row_mask:0xf bank_mask:0xf
	s_nop 1
	v_add_f32_dpp v242, v242, v242 row_ror:4 row_mask:0xf bank_mask:0xf
	s_nop 1
	v_add_f32_dpp v242, v242, v242 row_ror:8 row_mask:0xf bank_mask:0xf
	s_nop 1
	v_readlane_b32 s96, v242, 0
	v_readlane_b32 s97, v242, 16
	v_readlane_b32 s98, v242, 32
	v_readlane_b32 s99, v242, 48
	v_mov_b32_e32 v240, s96
	v_add_f32_e32 v240, s97, v240
	v_add_f32_e32 v240, s98, v240
	v_add_f32_e32 v240, s99, v240
	v_add_f32_dpp v243, v19, v19 quad_perm:[1,0,3,2] row_mask:0xf bank_mask:0xf
	s_nop 1
	v_add_f32_dpp v243, v243, v243 quad_perm:[2,3,0,1] row_mask:0xf bank_mask:0xf
	s_nop 1
	v_add_f32_dpp v243, v243, v243 row_ror:4 row_mask:0xf bank_mask:0xf
	s_nop 1
	v_add_f32_dpp v243, v243, v243 row_ror:8 row_mask:0xf bank_mask:0xf
	s_nop 1
	v_readlane_b32 s96, v243, 0
	v_readlane_b32 s97, v243, 16
	v_readlane_b32 s98, v243, 32
	v_readlane_b32 s99, v243, 48
	v_mov_b32_e32 v241, s96
	v_add_f32_e32 v241, s97, v241
	v_add_f32_e32 v241, s98, v241
	v_add_f32_e32 v241, s99, v241
	v_rcp_f32_e32 v14, v14
	v_mul_f32_e32 v0, v16, v0
	s_movk_i32 s91, 0xfff
	s_mov_b32 s33, 0x2aaaaaab
	s_waitcnt lgkmcnt(0)
	v_mul_f32_e32 v13, v14, v13
	v_mul_f32_e32 v0, v13, v0
	v_bfe_u32 v13, v0, 16, 1
	v_add3_u32 v0, v0, v13, s27
	s_waitcnt lgkmcnt(0)
	global_store_short_d16_hi v[8:9], v0, off offset:128
	v_lshlrev_b32_e32 v0, 16, v70
	v_mul_f32_e32 v8, 0xbfb8aa3b, v0
	v_exp_f32_e32 v13, v8
	s_waitcnt lgkmcnt(0)
	v_add_f32_e32 v13, 1.0, v13
	v_rcp_f32_e32 v13, v13
	v_lshlrev_b32_e32 v14, 16, v69
	v_add_u32_e32 v28, s18, v77
	s_waitcnt lgkmcnt(0)
	v_mul_f32_e32 v0, v13, v0
	v_mul_f32_e32 v13, 0xbfb8aa3b, v14
	v_exp_f32_e32 v13, v13
	v_ashrrev_i32_e32 v29, 31, v28
	s_waitcnt lgkmcnt(0)
	v_add_f32_e32 v13, 1.0, v13
	v_rcp_f32_e32 v13, v13
	v_lshlrev_b64 v[28:29], 11, v[28:29]
	v_lshl_add_u64 v[28:29], v[2:3], 0, v[28:29]
	s_waitcnt lgkmcnt(0)
	v_mov_b32_e32 v8, v240
	v_mov_b32_e32 v9, v241
	v_mul_f32_e32 v13, v13, v14
	v_pk_fma_f32 v[8:9], v[8:9], s[0:1], v[4:5] op_sel_hi:[1,0,0]
	v_add_u32_e32 v14, s18, v75
	v_mul_f32_e32 v18, 0x4b800000, v9
	v_cmp_gt_f32_e32 vcc, s87, v9
	v_cmp_gt_f32_e64 s[40:41], s87, v8
	v_readlane_b32 s93, v253, 29
	v_cndmask_b32_e32 v9, v9, v18, vcc
	v_rsq_f32_e32 v9, v9
	s_mov_b64 s[94:95], 0x400
	s_mov_b64 s[60:61], 0x1000
	v_readlane_b32 s46, v254, 33
	v_mul_f32_e32 v18, 0x45800000, v9
	v_cndmask_b32_e32 v9, v9, v18, vcc
	v_mul_f32_e32 v15, v15, v9
	v_mul_f32_e32 v15, v17, v15
	v_mul_f32_e32 v0, v0, v15
	v_bfe_u32 v15, v0, 16, 1
	v_add3_u32 v0, v0, v15, s27
	global_store_short_d16_hi v[28:29], v0, off
	v_mul_f32_e32 v0, v10, v9
	v_mul_f32_e32 v0, v16, v0
	v_mul_f32_e32 v0, v13, v0
	v_bfe_u32 v9, v0, 16, 1
	v_add3_u32 v0, v0, v9, s27
	v_mul_f32_e32 v9, 0x4b800000, v8
	v_cndmask_b32_e64 v8, v8, v9, s[40:41]
	v_lshlrev_b32_e32 v9, 16, v68
	v_rsq_f32_e32 v8, v8
	v_mul_f32_e32 v10, 0xbfb8aa3b, v9
	v_exp_f32_e32 v10, v10
	global_store_short_d16_hi v[28:29], v0, off offset:128
	v_mul_f32_e32 v0, 0x45800000, v8
	v_cndmask_b32_e64 v18, v8, v0, s[40:41]
	v_add_f32_e32 v0, 1.0, v10
	v_rcp_f32_e32 v8, v0
	v_mul_f32_e32 v10, v11, v18
	v_mul_f32_e32 v10, v17, v10
	v_ashrrev_i32_e32 v15, 31, v14
	v_mul_f32_e32 v8, v8, v9
	v_mul_f32_e32 v8, v8, v10
	v_bfe_u32 v9, v8, 16, 1
	v_add3_u32 v13, v8, v9, s27
	v_lshlrev_b64 v[8:9], 11, v[14:15]
	v_lshlrev_b32_e32 v0, 16, v67
	v_lshl_add_u64 v[10:11], v[2:3], 0, v[8:9]
	v_add_u32_e32 v8, 0xa00, v12
	global_store_short_d16_hi v[10:11], v13, off
	ds_read2_b32 v[8:9], v8 offset0:84 offset1:152
	v_mul_f32_e32 v13, 0xbfb8aa3b, v0
	v_exp_f32_e32 v19, v13
	ds_read_b32 v13, v12 offset:3424
	v_mov_b32_e32 v14, v7
	s_waitcnt lgkmcnt(1)
	v_mov_b32_e32 v15, v8
	v_mov_b32_e32 v12, v9
	v_pk_mul_f32 v[14:15], v[14:15], v[14:15]
	s_waitcnt lgkmcnt(0)
	v_pk_mul_f32 v[28:29], v[12:13], v[12:13]
	v_mov_b32_e32 v31, v14
	v_mov_b32_e32 v30, v28
	v_mov_b32_e32 v14, v29
	v_pk_add_f32 v[14:15], v[30:31], v[14:15]
	s_nop 1
	v_add_f32_dpp v242, v14, v14 quad_perm:[1,0,3,2] row_mask:0xf bank_mask:0xf
	s_nop 1
	v_add_f32_dpp v242, v242, v242 quad_perm:[2,3,0,1] row_mask:0xf bank_mask:0xf
	s_nop 1
	v_add_f32_dpp v242, v242, v242 row_ror:4 row_mask:0xf bank_mask:0xf
	s_nop 1
	v_add_f32_dpp v242, v242, v242 row_ror:8 row_mask:0xf bank_mask:0xf
	s_nop 1
	v_readlane_b32 s96, v242, 0
	v_readlane_b32 s97, v242, 16
	v_readlane_b32 s98, v242, 32
	v_readlane_b32 s99, v242, 48
	v_mov_b32_e32 v240, s96
	v_add_f32_e32 v240, s97, v240
	v_add_f32_e32 v240, s98, v240
	v_add_f32_e32 v240, s99, v240
	v_add_f32_dpp v243, v15, v15 quad_perm:[1,0,3,2] row_mask:0xf bank_mask:0xf
	s_nop 1
	v_add_f32_dpp v243, v243, v243 quad_perm:[2,3,0,1] row_mask:0xf bank_mask:0xf
	s_nop 1
	v_add_f32_dpp v243, v243, v243 row_ror:4 row_mask:0xf bank_mask:0xf
	s_nop 1
	v_add_f32_dpp v243, v243, v243 row_ror:8 row_mask:0xf bank_mask:0xf
	s_nop 1
	v_readlane_b32 s96, v243, 0
	v_readlane_b32 s97, v243, 16
	v_readlane_b32 s98, v243, 32
	v_readlane_b32 s99, v243, 48
	v_mov_b32_e32 v241, s96
	v_add_f32_e32 v241, s97, v241
	v_add_f32_e32 v241, s98, v241
	v_add_f32_e32 v241, s99, v241
	v_mul_f32_e32 v6, v6, v18
	v_add_f32_e32 v12, 1.0, v19
	v_rcp_f32_e32 v12, v12
	v_mul_f32_e32 v6, v16, v6
	s_waitcnt lgkmcnt(0)
	v_mul_f32_e32 v0, v12, v0
	v_mul_f32_e32 v0, v0, v6
	v_bfe_u32 v6, v0, 16, 1
	v_add3_u32 v0, v0, v6, s27
	s_waitcnt lgkmcnt(0)
	global_store_short_d16_hi v[10:11], v0, off offset:128
	v_lshlrev_b32_e32 v0, 16, v64
	v_mul_f32_e32 v6, 0xbfb8aa3b, v0
	v_exp_f32_e32 v6, v6
	s_waitcnt lgkmcnt(0)
	v_add_f32_e32 v6, 1.0, v6
	v_rcp_f32_e32 v6, v6
	v_lshlrev_b32_e32 v12, 16, v63
	v_add_u32_e32 v18, s18, v66
	s_waitcnt lgkmcnt(0)
	v_mul_f32_e32 v0, v6, v0
	v_mul_f32_e32 v6, 0xbfb8aa3b, v12
	v_exp_f32_e32 v6, v6
	v_ashrrev_i32_e32 v19, 31, v18
	s_waitcnt lgkmcnt(0)
	v_add_f32_e32 v6, 1.0, v6
	v_rcp_f32_e32 v6, v6
	v_lshlrev_b64 v[18:19], 11, v[18:19]
	v_lshl_add_u64 v[18:19], v[2:3], 0, v[18:19]
	s_waitcnt lgkmcnt(0)
	v_mov_b32_e32 v10, v240
	v_mov_b32_e32 v11, v241
	v_readlane_b32 s71, v254, 35
	v_pk_fma_f32 v[4:5], v[10:11], s[0:1], v[4:5] op_sel_hi:[1,0,0]
	v_readlane_b32 s72, v254, 36
	v_mul_f32_e32 v10, 0x4b800000, v5
	v_cmp_gt_f32_e32 vcc, s87, v5
	v_cmp_gt_f32_e64 s[40:41], s87, v4
	v_readlane_b32 s75, v254, 38
	v_cndmask_b32_e32 v5, v5, v10, vcc
	v_rsq_f32_e32 v5, v5
	v_mul_f32_e32 v10, v6, v12
	v_add_u32_e32 v6, s18, v65
	v_readlane_b32 s59, v254, 45
	v_mul_f32_e32 v11, 0x45800000, v5
	v_cndmask_b32_e32 v5, v5, v11, vcc
	v_mul_f32_e32 v7, v7, v5
	v_mul_f32_e32 v7, v17, v7
	v_mul_f32_e32 v0, v0, v7
	v_bfe_u32 v7, v0, 16, 1
	v_add3_u32 v0, v0, v7, s27
	global_store_short_d16_hi v[18:19], v0, off
	v_mul_f32_e32 v0, v8, v5
	v_mul_f32_e32 v0, v16, v0
	v_mul_f32_e32 v0, v10, v0
	v_bfe_u32 v5, v0, 16, 1
	v_add3_u32 v0, v0, v5, s27
	v_mul_f32_e32 v5, 0x4b800000, v4
	v_cndmask_b32_e64 v4, v4, v5, s[40:41]
	v_lshlrev_b32_e32 v5, 16, v62
	v_rsq_f32_e32 v4, v4
	v_mul_f32_e32 v7, 0xbfb8aa3b, v5
	v_exp_f32_e32 v7, v7
	global_store_short_d16_hi v[18:19], v0, off offset:128
	v_mul_f32_e32 v0, 0x45800000, v4
	v_cndmask_b32_e64 v0, v4, v0, s[40:41]
	v_add_f32_e32 v4, 1.0, v7
	v_rcp_f32_e32 v4, v4
	v_mul_f32_e32 v7, v9, v0
	v_mul_f32_e32 v7, v17, v7
	v_lshlrev_b32_e32 v8, 16, v21
	v_mul_f32_e32 v4, v4, v5
	v_mul_f32_e32 v4, v4, v7
	v_bfe_u32 v5, v4, 16, 1
	v_add3_u32 v9, v4, v5, s27
	v_mul_f32_e32 v4, 0xbfb8aa3b, v8
	v_exp_f32_e32 v10, v4
	v_ashrrev_i32_e32 v7, 31, v6
	v_lshlrev_b64 v[4:5], 11, v[6:7]
	v_lshl_add_u64 v[2:3], v[2:3], 0, v[4:5]
	v_add_f32_e32 v4, 1.0, v10
	v_rcp_f32_e32 v4, v4
	v_mul_f32_e32 v0, v13, v0
	v_mul_f32_e32 v0, v16, v0
	global_store_short_d16_hi v[2:3], v9, off
	v_mul_f32_e32 v4, v4, v8
	v_mul_f32_e32 v0, v4, v0
	v_bfe_u32 v4, v0, 16, 1
	v_add3_u32 v0, v0, v4, s27
	global_store_short_d16_hi v[2:3], v0, off offset:128
	s_barrier
	v_readlane_b32 s73, v254, 46

.LBB0_675:
	s_and_b64 s[10:11], vcc, exec
	s_movk_i32 s4, 0x68
	s_cselect_b32 s4, s4, 0x78
	s_add_u32 s10, s8, s4
	s_addc_u32 s11, s9, 0
	s_waitcnt lgkmcnt(0)
	s_barrier
	v_and_b32_e32 v3, 63, v2
	v_lshlrev_b32_e32 v0, 2, v3
	s_waitcnt lgkmcnt(0)
	s_add_u32 s4, s10, s22
	s_addc_u32 s5, s11, s23
	s_lshl_b32 s7, s6, 2
	s_add_u32 s10, s4, s7
	s_addc_u32 s11, s5, 0
	v_lshl_add_u64 v[8:9], s[10:11], 0, v[0:1]
	v_add_co_u32_e64 v34, s[40:41], s37, v8
	s_and_b64 s[14:15], vcc, exec
	s_nop 0
	v_addc_co_u32_e64 v35, s[40:41], 0, v9, s[40:41]
	s_movk_i32 s4, 0x70
	v_add_co_u32_e64 v36, s[40:41], s85, v8
	s_cselect_b32 s4, s4, 0x80
	s_nop 0
	v_addc_co_u32_e64 v37, s[40:41], 0, v9, s[40:41]
	s_add_u32 s14, s8, s4
	v_add_co_u32_e64 v26, s[40:41], s68, v8
	s_addc_u32 s15, s9, 0
	v_addc_co_u32_e64 v27, s[40:41], 0, v9, s[40:41]
	v_readlane_b32 s4, v254, 41
	s_or_b32 s4, s6, s4
	v_or_b32_e32 v26, s4, v3
	v_mov_b32_e32 v27, v1
	s_waitcnt lgkmcnt(0)
	v_lshl_add_u64 v[26:27], v[26:27], 2, s[14:15]
	s_nop 0
	s_waitcnt vmcnt(0)
	v_mov_b32_e32 v29, v132
	v_mov_b32_e32 v30, v133
	v_mov_b32_e32 v31, v134
	v_mov_b32_e32 v32, v135
	v_mov_b32_e32 v28, v136
	v_mov_b32_e32 v27, v137
	v_mov_b32_e32 v12, v138
	v_mov_b32_e32 v13, v139
	v_mov_b32_e32 v6, v140
	v_mov_b32_e32 v7, v141
	v_mov_b32_e32 v4, v142
	v_mov_b32_e32 v5, v143
	v_mov_b32_e32 v8, v144
	v_mov_b32_e32 v9, v145
	v_mov_b32_e32 v10, v146
	v_mov_b32_e32 v11, v147
	v_mov_b32_e32 v26, v148
	v_ashrrev_i32_e32 v3, 6, v2
	v_lshl_add_u32 v25, v3, 9, 0
	ds_read_b128 v[34:37], v25 offset:27664
	ds_read_b128 v[38:41], v25 offset:27680
	ds_read_b128 v[42:45], v25 offset:27696
	ds_read_b128 v[46:49], v25 offset:27648
	s_mov_b32 s4, 0x3d800000
	v_lshl_add_u32 v2, v2, 2, 0
	v_add_u32_e32 v0, 0, v0
	v_readlane_b32 s5, v254, 42
	s_waitcnt vmcnt(15) lgkmcnt(2)
	v_pk_mul_f32 v[38:39], v[6:7], v[38:39]
	s_waitcnt vmcnt(13)
	v_pk_mul_f32 v[40:41], v[4:5], v[40:41]
	s_waitcnt vmcnt(11)
	v_pk_mul_f32 v[36:37], v[12:13], v[36:37]
	s_waitcnt vmcnt(9) lgkmcnt(1)
	v_pk_mul_f32 v[42:43], v[8:9], v[42:43]
	s_waitcnt vmcnt(5) lgkmcnt(0)
	v_fma_f32 v33, v29, v46, v26
	s_waitcnt vmcnt(4)
	v_fmac_f32_e32 v33, v30, v47
	s_waitcnt vmcnt(3)
	v_fmac_f32_e32 v33, v31, v48
	s_waitcnt vmcnt(2)
	v_fmac_f32_e32 v33, v32, v49
	s_waitcnt vmcnt(1)
	v_fmac_f32_e32 v33, v28, v34
	s_waitcnt vmcnt(0)
	v_fmac_f32_e32 v33, v27, v35
	v_add_f32_e32 v33, v33, v36
	v_add_f32_e32 v33, v33, v37
	v_add_f32_e32 v33, v33, v38
	v_add_f32_e32 v33, v33, v39
	v_add_f32_e32 v33, v33, v40
	v_add_f32_e32 v33, v33, v41
	v_add_f32_e32 v33, v33, v42
	v_pk_mul_f32 v[44:45], v[10:11], v[44:45]
	v_add_f32_e32 v33, v33, v43
	v_add_f32_e32 v33, v33, v44
	v_add_f32_e32 v33, v33, v45
	v_mul_f32_e64 v34, |v33|, s90
	v_exp_f32_e32 v38, v34
	v_min_f32_e32 v33, 0, v33
	s_nop 1
	s_nop 1
	ds_read_b128 v[34:37], v25 offset:27712
	s_nop 1
	s_nop 1
	v_add_f32_e32 v150, 1.0, v38
	s_nop 0
	v_add_f32_e32 v151, -1.0, v150
	v_log_f32_e32 v152, v150
	v_rcp_f32_e32 v153, v151
	s_nop 0
	v_mul_f32_e32 v152, 0x3f317218, v152
	v_mul_f32_e32 v153, v38, v153
	v_cmp_eq_f32_e32 vcc, 0, v151
	v_mul_f32_e32 v152, v152, v153
	s_nop 0
	v_cndmask_b32_e32 v42, v152, v38, vcc
	ds_read_b128 v[38:41], v25 offset:27728
	s_waitcnt lgkmcnt(1)
	v_fma_f32 v43, v29, v34, v26
	v_fmac_f32_e32 v43, v30, v35
	v_fmac_f32_e32 v43, v31, v36
	v_fmac_f32_e32 v43, v32, v37
	ds_read_b128 v[34:37], v25 offset:27744
	s_waitcnt lgkmcnt(1)
	v_fmac_f32_e32 v43, v28, v38
	v_fmac_f32_e32 v43, v27, v39
	v_pk_mul_f32 v[38:39], v[12:13], v[40:41]
	v_sub_f32_e32 v33, v33, v42
	v_add_f32_e32 v38, v43, v38
	v_add_f32_e32 v43, v38, v39
	ds_read_b128 v[38:41], v25 offset:27760
	s_waitcnt lgkmcnt(1)
	v_pk_mul_f32 v[34:35], v[6:7], v[34:35]
	v_fma_f32 v33, v33, s4, 0
	v_add_f32_e32 v34, v43, v34
	v_add_f32_e32 v43, v34, v35
	v_pk_mul_f32 v[34:35], v[4:5], v[36:37]
	s_nop 0
	v_add_f32_e32 v34, v43, v34
	v_add_f32_e32 v36, v34, v35
	s_waitcnt lgkmcnt(0)
	v_pk_mul_f32 v[34:35], v[8:9], v[38:39]
	s_nop 0
	v_add_f32_e32 v34, v36, v34
	v_add_f32_e32 v36, v34, v35
	v_pk_mul_f32 v[34:35], v[10:11], v[40:41]
	s_nop 0
	v_add_f32_e32 v34, v36, v34
	v_add_f32_e32 v34, v34, v35
	v_mul_f32_e64 v35, |v34|, s90
	v_exp_f32_e32 v38, v35
	v_min_f32_e32 v42, 0, v34
	s_nop 1
	s_nop 1
	s_nop 1
	ds_read_b128 v[34:37], v25 offset:27776
	s_nop 1
	s_nop 1
	v_add_f32_e32 v150, 1.0, v38
	s_nop 0
	v_add_f32_e32 v151, -1.0, v150
	v_log_f32_e32 v152, v150
	v_rcp_f32_e32 v153, v151
	s_nop 0
	v_mul_f32_e32 v152, 0x3f317218, v152
	v_mul_f32_e32 v153, v38, v153
	v_cmp_eq_f32_e32 vcc, 0, v151
	v_mul_f32_e32 v152, v152, v153
	s_nop 0
	v_cndmask_b32_e32 v43, v152, v38, vcc
	ds_read_b128 v[38:41], v25 offset:27792
	s_waitcnt lgkmcnt(1)
	v_fma_f32 v44, v29, v34, v26
	v_fmac_f32_e32 v44, v30, v35
	v_fmac_f32_e32 v44, v31, v36
	v_fmac_f32_e32 v44, v32, v37
	ds_read_b128 v[34:37], v25 offset:27808
	s_waitcnt lgkmcnt(1)
	v_fmac_f32_e32 v44, v28, v38
	v_fmac_f32_e32 v44, v27, v39
	v_pk_mul_f32 v[38:39], v[12:13], v[40:41]
	s_nop 0
	v_add_f32_e32 v38, v44, v38
	v_add_f32_e32 v44, v38, v39
	ds_read_b128 v[38:41], v25 offset:27824
	s_waitcnt lgkmcnt(1)
	v_pk_mul_f32 v[34:35], v[6:7], v[34:35]
	s_nop 0
	v_add_f32_e32 v34, v44, v34
	v_add_f32_e32 v44, v34, v35
	v_pk_mul_f32 v[34:35], v[4:5], v[36:37]
	s_nop 0
	v_add_f32_e32 v34, v44, v34
	v_add_f32_e32 v36, v34, v35
	s_waitcnt lgkmcnt(0)
	v_pk_mul_f32 v[34:35], v[8:9], v[38:39]
	s_nop 0
	v_add_f32_e32 v34, v36, v34
	v_add_f32_e32 v36, v34, v35
	v_pk_mul_f32 v[34:35], v[10:11], v[40:41]
	s_nop 0
	v_add_f32_e32 v34, v36, v34
	v_add_f32_e32 v35, v34, v35
	v_mul_f32_e64 v34, |v35|, s90
	v_exp_f32_e32 v40, v34
	v_sub_f32_e32 v34, v42, v43
	v_min_f32_e32 v35, 0, v35
	v_fmamk_f32 v34, v34, 0x3d800000, v33
	s_nop 1
	s_nop 1
	s_nop 1
	ds_read_b128 v[36:39], v25 offset:27840
	s_nop 1
	s_nop 1
	v_add_f32_e32 v150, 1.0, v40
	s_nop 0
	v_add_f32_e32 v151, -1.0, v150
	v_log_f32_e32 v152, v150
	v_rcp_f32_e32 v153, v151
	s_nop 0
	v_mul_f32_e32 v152, 0x3f317218, v152
	v_mul_f32_e32 v153, v40, v153
	v_cmp_eq_f32_e32 vcc, 0, v151
	v_mul_f32_e32 v152, v152, v153
	s_nop 0
	v_cndmask_b32_e32 v44, v152, v40, vcc
	ds_read_b128 v[40:43], v25 offset:27856
	s_waitcnt lgkmcnt(1)
	v_fma_f32 v45, v29, v36, v26
	v_fmac_f32_e32 v45, v30, v37
	v_fmac_f32_e32 v45, v31, v38
	v_fmac_f32_e32 v45, v32, v39
	ds_read_b128 v[36:39], v25 offset:27872
	s_waitcnt lgkmcnt(1)
	v_fmac_f32_e32 v45, v28, v40
	v_fmac_f32_e32 v45, v27, v41
	v_pk_mul_f32 v[40:41], v[12:13], v[42:43]
	v_sub_f32_e32 v35, v35, v44
	v_add_f32_e32 v40, v45, v40
	v_add_f32_e32 v45, v40, v41
	ds_read_b128 v[40:43], v25 offset:27888
	s_waitcnt lgkmcnt(1)
	v_pk_mul_f32 v[36:37], v[6:7], v[36:37]
	v_fmamk_f32 v35, v35, 0x3d800000, v34
	v_add_f32_e32 v36, v45, v36
	v_add_f32_e32 v45, v36, v37
	v_pk_mul_f32 v[36:37], v[4:5], v[38:39]
	s_nop 0
	v_add_f32_e32 v36, v45, v36
	v_add_f32_e32 v38, v36, v37
	s_waitcnt lgkmcnt(0)
	v_pk_mul_f32 v[36:37], v[8:9], v[40:41]
	s_nop 0
	v_add_f32_e32 v36, v38, v36
	v_add_f32_e32 v38, v36, v37
	v_pk_mul_f32 v[36:37], v[10:11], v[42:43]
	s_nop 0
	v_add_f32_e32 v36, v38, v36
	v_add_f32_e32 v36, v36, v37
	v_mul_f32_e64 v37, |v36|, s90
	v_exp_f32_e32 v40, v37
	v_min_f32_e32 v44, 0, v36
	s_nop 1
	s_nop 1
	s_nop 1
	ds_read_b128 v[36:39], v25 offset:27904
	s_nop 1
	s_nop 1
	v_add_f32_e32 v150, 1.0, v40
	s_nop 0
	v_add_f32_e32 v151, -1.0, v150
	v_log_f32_e32 v152, v150
	v_rcp_f32_e32 v153, v151
	s_nop 0
	v_mul_f32_e32 v152, 0x3f317218, v152
	v_mul_f32_e32 v153, v40, v153
	v_cmp_eq_f32_e32 vcc, 0, v151
	v_mul_f32_e32 v152, v152, v153
	s_nop 0
	v_cndmask_b32_e32 v45, v152, v40, vcc
	ds_read_b128 v[40:43], v25 offset:27920
	s_waitcnt lgkmcnt(1)
	v_fma_f32 v46, v29, v36, v26
	v_fmac_f32_e32 v46, v30, v37
	v_fmac_f32_e32 v46, v31, v38
	v_fmac_f32_e32 v46, v32, v39
	ds_read_b128 v[36:39], v25 offset:27936
	s_waitcnt lgkmcnt(1)
	v_fmac_f32_e32 v46, v28, v40
	v_fmac_f32_e32 v46, v27, v41
	v_pk_mul_f32 v[40:41], v[12:13], v[42:43]
	s_nop 0
	v_add_f32_e32 v40, v46, v40
	v_add_f32_e32 v46, v40, v41
	ds_read_b128 v[40:43], v25 offset:27952
	s_waitcnt lgkmcnt(1)
	v_pk_mul_f32 v[36:37], v[6:7], v[36:37]
	s_nop 0
	v_add_f32_e32 v36, v46, v36
	v_add_f32_e32 v46, v36, v37
	v_pk_mul_f32 v[36:37], v[4:5], v[38:39]
	s_nop 0
	v_add_f32_e32 v36, v46, v36
	v_add_f32_e32 v38, v36, v37
	s_waitcnt lgkmcnt(0)
	v_pk_mul_f32 v[36:37], v[8:9], v[40:41]
	s_nop 0
	v_add_f32_e32 v36, v38, v36
	v_add_f32_e32 v38, v36, v37
	v_pk_mul_f32 v[36:37], v[10:11], v[42:43]
	s_nop 0
	v_add_f32_e32 v36, v38, v36
	v_add_f32_e32 v37, v36, v37
	v_mul_f32_e64 v36, |v37|, s90
	v_exp_f32_e32 v42, v36
	v_sub_f32_e32 v36, v44, v45
	v_min_f32_e32 v37, 0, v37
	v_fmamk_f32 v36, v36, 0x3d800000, v35
	s_nop 1
	s_nop 1
	s_nop 1
	ds_read_b128 v[38:41], v25 offset:27968
	s_nop 1
	s_nop 1
	v_add_f32_e32 v150, 1.0, v42
	s_nop 0
	v_add_f32_e32 v151, -1.0, v150
	v_log_f32_e32 v152, v150
	v_rcp_f32_e32 v153, v151
	s_nop 0
	v_mul_f32_e32 v152, 0x3f317218, v152
	v_mul_f32_e32 v153, v42, v153
	v_cmp_eq_f32_e32 vcc, 0, v151
	v_mul_f32_e32 v152, v152, v153
	s_nop 0
	v_cndmask_b32_e32 v46, v152, v42, vcc
	ds_read_b128 v[42:45], v25 offset:27984
	s_waitcnt lgkmcnt(1)
	v_fma_f32 v47, v29, v38, v26
	v_fmac_f32_e32 v47, v30, v39
	v_fmac_f32_e32 v47, v31, v40
	v_fmac_f32_e32 v47, v32, v41
	ds_read_b128 v[38:41], v25 offset:28000
	s_waitcnt lgkmcnt(1)
	v_fmac_f32_e32 v47, v28, v42
	v_fmac_f32_e32 v47, v27, v43
	v_pk_mul_f32 v[42:43], v[12:13], v[44:45]
	v_sub_f32_e32 v37, v37, v46
	v_add_f32_e32 v42, v47, v42
	v_add_f32_e32 v47, v42, v43
	ds_read_b128 v[42:45], v25 offset:28016
	s_waitcnt lgkmcnt(1)
	v_pk_mul_f32 v[38:39], v[6:7], v[38:39]
	v_fmamk_f32 v37, v37, 0x3d800000, v36
	v_add_f32_e32 v38, v47, v38
	v_add_f32_e32 v47, v38, v39
	v_pk_mul_f32 v[38:39], v[4:5], v[40:41]
	s_nop 0
	v_add_f32_e32 v38, v47, v38
	v_add_f32_e32 v40, v38, v39
	s_waitcnt lgkmcnt(0)
	v_pk_mul_f32 v[38:39], v[8:9], v[42:43]
	s_nop 0
	v_add_f32_e32 v38, v40, v38
	v_add_f32_e32 v40, v38, v39
	v_pk_mul_f32 v[38:39], v[10:11], v[44:45]
	s_nop 0
	v_add_f32_e32 v38, v40, v38
	v_add_f32_e32 v38, v38, v39
	v_mul_f32_e64 v39, |v38|, s90
	v_exp_f32_e32 v52, v39
	v_min_f32_e32 v53, 0, v38
	s_nop 1
	s_nop 0
	s_nop 0
	s_nop 0
	s_nop 0
	s_nop 0
	s_nop 1
	ds_read_b128 v[38:41], v25 offset:28032
	s_nop 1
	s_nop 1
	v_add_f32_e32 v150, 1.0, v52
	s_nop 0
	v_add_f32_e32 v151, -1.0, v150
	v_log_f32_e32 v152, v150
	v_rcp_f32_e32 v153, v151
	s_nop 0
	v_mul_f32_e32 v152, 0x3f317218, v152
	v_mul_f32_e32 v153, v52, v153
	v_cmp_eq_f32_e32 vcc, 0, v151
	v_mul_f32_e32 v152, v152, v153
	s_nop 0
	v_cndmask_b32_e32 v46, v152, v52, vcc
	ds_read_b128 v[42:45], v25 offset:28048
	s_waitcnt lgkmcnt(1)
	v_fma_f32 v47, v29, v38, v26
	v_fmac_f32_e32 v47, v30, v39
	v_fmac_f32_e32 v47, v31, v40
	v_fmac_f32_e32 v47, v32, v41
	ds_read_b128 v[38:41], v25 offset:28064
	s_waitcnt lgkmcnt(1)
	v_fmac_f32_e32 v47, v28, v42
	v_fmac_f32_e32 v47, v27, v43
	v_pk_mul_f32 v[42:43], v[12:13], v[44:45]
	s_nop 0
	v_add_f32_e32 v42, v47, v42
	v_add_f32_e32 v47, v42, v43
	ds_read_b128 v[42:45], v25 offset:28080
	s_waitcnt lgkmcnt(1)
	v_pk_mul_f32 v[38:39], v[6:7], v[38:39]
	s_nop 0
	v_add_f32_e32 v38, v47, v38
	v_add_f32_e32 v47, v38, v39
	v_pk_mul_f32 v[38:39], v[4:5], v[40:41]
	s_nop 0
	v_add_f32_e32 v38, v47, v38
	v_add_f32_e32 v40, v38, v39
	s_waitcnt lgkmcnt(0)
	v_pk_mul_f32 v[38:39], v[8:9], v[42:43]
	s_nop 0
	v_add_f32_e32 v38, v40, v38
	v_add_f32_e32 v40, v38, v39
	v_pk_mul_f32 v[38:39], v[10:11], v[44:45]
	s_nop 0
	v_add_f32_e32 v38, v40, v38
	v_add_f32_e32 v38, v38, v39
	v_mul_f32_e64 v39, |v38|, s90
	v_exp_f32_e32 v52, v39
	v_sub_f32_e32 v39, v53, v46
	v_min_f32_e32 v54, 0, v38
	v_fmamk_f32 v53, v39, 0x3d800000, v37
	s_nop 1
	s_nop 0
	s_nop 0
	s_nop 0
	s_nop 0
	s_nop 0
	s_nop 1
	ds_read_b128 v[38:41], v25 offset:28096
	s_nop 1
	s_nop 1
	v_add_f32_e32 v150, 1.0, v52
	s_nop 0
	v_add_f32_e32 v151, -1.0, v150
	v_log_f32_e32 v152, v150
	v_rcp_f32_e32 v153, v151
	s_nop 0
	v_mul_f32_e32 v152, 0x3f317218, v152
	v_mul_f32_e32 v153, v52, v153
	v_cmp_eq_f32_e32 vcc, 0, v151
	v_mul_f32_e32 v152, v152, v153
	s_nop 0
	v_cndmask_b32_e32 v46, v152, v52, vcc
	ds_read_b128 v[42:45], v25 offset:28112
	s_waitcnt lgkmcnt(1)
	v_fmac_f32_e32 v26, v29, v38
	v_fmac_f32_e32 v26, v30, v39
	v_fmac_f32_e32 v26, v31, v40
	v_fmac_f32_e32 v26, v32, v41
	s_waitcnt lgkmcnt(0)
	v_fmac_f32_e32 v26, v28, v42
	ds_read_b128 v[28:31], v25 offset:28128
	ds_read_b128 v[38:41], v25 offset:28144
	v_fmac_f32_e32 v26, v27, v43
	v_pk_mul_f32 v[12:13], v[12:13], v[44:45]
	s_waitcnt lgkmcnt(1)
	v_pk_mul_f32 v[6:7], v[6:7], v[28:29]
	v_add_f32_e32 v12, v26, v12
	v_add_f32_e32 v12, v12, v13
	v_add_f32_e32 v6, v12, v6
	v_add_f32_e32 v6, v6, v7
	v_pk_mul_f32 v[4:5], v[4:5], v[30:31]
	s_nop 0
	v_add_f32_e32 v4, v6, v4
	v_add_f32_e32 v6, v4, v5
	s_waitcnt lgkmcnt(0)
	v_pk_mul_f32 v[4:5], v[8:9], v[38:39]
	s_nop 0
	v_add_f32_e32 v4, v6, v4
	v_add_f32_e32 v6, v4, v5
	v_pk_mul_f32 v[4:5], v[10:11], v[40:41]
	s_nop 0
	v_add_f32_e32 v4, v6, v4
	v_add_f32_e32 v4, v4, v5
	v_mul_f32_e64 v5, |v4|, s90
	v_exp_f32_e32 v25, v5
	v_sub_f32_e32 v5, v54, v46
	v_min_f32_e32 v31, 0, v4
	v_fmamk_f32 v30, v5, 0x3d800000, v53
	s_nop 1
	s_nop 0
	s_nop 0
	s_nop 0
	s_nop 0
	s_nop 0
	s_nop 1
	s_nop 1
	s_nop 1
	v_add_f32_e32 v150, 1.0, v25
	s_nop 0
	v_add_f32_e32 v151, -1.0, v150
	v_log_f32_e32 v152, v150
	v_rcp_f32_e32 v153, v151
	s_nop 0
	v_mul_f32_e32 v152, 0x3f317218, v152
	v_mul_f32_e32 v153, v25, v153
	v_cmp_eq_f32_e32 vcc, 0, v151
	v_mul_f32_e32 v152, v152, v153
	s_nop 0
	v_cndmask_b32_e32 v4, v152, v25, vcc
	v_sub_f32_e32 v4, v31, v4
	v_fmamk_f32 v5, v4, 0x3d800000, v30
	ds_write_b32 v2, v5 offset:31744
	s_waitcnt lgkmcnt(0)
	s_barrier
	ds_read2st64_b32 v[6:7], v0 offset0:124 offset1:125
	ds_read2st64_b32 v[8:9], v0 offset0:126 offset1:127
	ds_read2st64_b32 v[10:11], v0 offset0:128 offset1:129
	ds_read2st64_b32 v[12:13], v0 offset0:130 offset1:131
	v_cmp_lt_i32_e32 vcc, 0, v3
	s_waitcnt lgkmcnt(3)
	v_add_f32_e32 v0, 0, v6
	s_waitcnt lgkmcnt(0)
	v_cndmask_b32_e32 v2, 0, v0, vcc
	v_add_f32_e32 v4, v7, v2
	v_cmp_lt_i32_e32 vcc, 1, v3
	v_add_f32_e32 v0, v0, v7
	v_add_f32_e32 v0, v0, v8
	v_cndmask_b32_e32 v2, v2, v4, vcc
	v_add_f32_e32 v4, v8, v2
	v_cmp_lt_i32_e32 vcc, 2, v3
	v_add_f32_e32 v0, v0, v9
	v_add_f32_e32 v0, v0, v10
	v_cndmask_b32_e32 v2, v2, v4, vcc
	v_add_f32_e32 v4, v9, v2
	v_cmp_lt_i32_e32 vcc, 3, v3
	v_add_f32_e32 v0, v0, v11
	v_lshlrev_b32_e32 v7, 16, v21
	v_cndmask_b32_e32 v2, v2, v4, vcc
	v_add_f32_e32 v4, v10, v2
	v_cmp_lt_i32_e32 vcc, 4, v3
	v_lshlrev_b32_e32 v9, 16, v22
	v_lshlrev_b32_e32 v8, 16, v17
	v_cndmask_b32_e32 v2, v2, v4, vcc
	v_add_f32_e32 v4, v11, v2
	v_cmp_lt_i32_e32 vcc, 5, v3
	v_lshlrev_b32_e32 v11, 16, v24
	v_lshlrev_b32_e32 v10, 16, v20
	v_cndmask_b32_e32 v2, v2, v4, vcc
	v_add_f32_e32 v4, v12, v2
	v_cmp_lt_i32_e32 vcc, 6, v3
	s_barrier
	s_nop 0
	v_cndmask_b32_e32 v2, v2, v4, vcc
	v_add_f32_e32 v4, v13, v2
	v_cmp_lt_i32_e32 vcc, 7, v3
	s_nop 1
	v_cndmask_b32_e32 v3, v2, v4, vcc
	v_add_f32_e32 v4, v0, v12
	v_mov_b32_e32 v2, v13
	v_add_f32_e32 v6, v33, v3
	v_add_f32_e32 v25, v34, v3
	v_add_f32_e32 v26, v35, v3
	v_add_f32_e32 v27, v36, v3
	v_add_f32_e32 v28, v3, v37
	v_add_f32_e32 v29, v3, v53
	v_add_f32_e32 v30, v3, v30
	v_pk_add_f32 v[2:3], v[4:5], v[2:3]
	v_mov_b32_e32 v80, v6
	v_mov_b32_e32 v81, v25
	v_mov_b32_e32 v82, v26
	v_mov_b32_e32 v83, v27
	v_mov_b32_e32 v84, v28
	v_mov_b32_e32 v85, v29
	v_mov_b32_e32 v86, v30
	v_mov_b32_e32 v87, v3
	v_lshlrev_b32_e32 v88, 5, v202
	s_lshl_b32 s98, s30, 14
	s_add_u32 s98, s98, 0x4f28000
	s_add_u32 s98, s100, s98
	s_addc_u32 s99, s101, 0
	global_store_dwordx4 v88, v[80:83], s[98:99]
	global_store_dwordx4 v88, v[84:87], s[98:99] offset:16
	v_cmp_gt_i32_e32 vcc, 64, v18
	v_sub_f32_e32 v0, v2, v6
	v_mul_f32_e32 v0, 0x3fb8aa3b, v0
	v_exp_f32_e32 v4, v0
	v_sub_f32_e32 v0, v2, v25
	v_mul_f32_e32 v0, 0x3fb8aa3b, v0
	v_exp_f32_e32 v5, v0
	v_sub_f32_e32 v0, v2, v26
	v_lshlrev_b32_e32 v6, 16, v16
	v_mul_f32_e32 v0, 0x3fb8aa3b, v0
	v_pk_mul_f32 v[4:5], v[4:5], v[6:7]
	v_exp_f32_e32 v6, v0
	v_sub_f32_e32 v0, v2, v27
	v_mul_f32_e32 v0, 0x3fb8aa3b, v0
	v_exp_f32_e32 v7, v0
	v_sub_f32_e32 v0, v2, v28
	v_mul_f32_e32 v0, 0x3fb8aa3b, v0
	v_cvt_pk_bf16_f32 v4, v4, v5
	v_pk_mul_f32 v[6:7], v[6:7], v[8:9]
	v_exp_f32_e32 v8, v0
	v_sub_f32_e32 v0, v2, v29
	v_mul_f32_e32 v0, 0x3fb8aa3b, v0
	v_exp_f32_e32 v9, v0
	v_sub_f32_e32 v0, v2, v30
	v_cvt_pk_bf16_f32 v5, v6, v7
	v_lshlrev_b32_e32 v7, 16, v23
	v_lshlrev_b32_e32 v6, 16, v19
	v_mul_f32_e32 v0, 0x3fb8aa3b, v0
	v_pk_mul_f32 v[6:7], v[8:9], v[6:7]
	v_exp_f32_e32 v8, v0
	v_sub_f32_e32 v0, v2, v3
	v_mul_f32_e32 v0, 0x3fb8aa3b, v0
	v_exp_f32_e32 v9, v0
	v_mul_u32_u24_e32 v0, 0x90, v15
	v_lshlrev_b32_e32 v3, 4, v14
	v_cvt_pk_bf16_f32 v6, v6, v7
	v_pk_mul_f32 v[8:9], v[8:9], v[10:11]
	v_add3_u32 v0, 0, v0, v3
	v_cvt_pk_bf16_f32 v7, v8, v9
	ds_write_b128 v0, v[4:7]
	s_and_saveexec_b64 s[14:15], vcc
	s_cbranch_execz .LBB0_677
	v_mul_f32_e32 v0, 0x3fb8aa3b, v2
	s_lshl_b64 s[6:7], s[30:31], 8
	v_readlane_b32 s4, v254, 53
	v_exp_f32_e32 v0, v0
	v_readlane_b32 s5, v254, 54
	s_add_u32 s6, s4, s6
	s_addc_u32 s7, s5, s7
	v_ashrrev_i32_e32 v19, 31, v18
	v_lshl_add_u64 v[2:3], v[18:19], 2, s[6:7]
	global_store_dword v[2:3], v0, off
